# P6 epilogue: 16-byte pieces moved by ds_bpermute so each lane quad stores a contiguous 64-byte run
# baseline (speedup 1.0000x reference)
.LBB0_783:
	s_lshl_b32 s98, s4, 8
	s_add_i32 s98, s98, s59
	s_lshl_b32 s98, s98, 13
	s_lshl_b32 s99, s5, 9
	s_add_u32 s98, s98, s99
	s_add_u32 s98, s98, s8
	s_add_u32 s98, s14, s98
	s_addc_u32 s99, s15, 0
	v_lshl_add_u32 v148, v150, 4, v1
	v_lshrrev_b32_e32 v149, 2, v148
	v_and_b32_e32 v148, 3, v148
	v_lshl_add_u32 v138, v148, 4, v149
	v_lshlrev_b32_e32 v138, 2, v138
	v_lshlrev_b32_e32 v149, 13, v149
	v_lshl_add_u32 v148, v148, 4, v149
	v_max_f32_e32 v122, 0, v122
	v_max_f32_e32 v123, 0, v123
	v_max_f32_e32 v124, 0, v124
	v_max_f32_e32 v125, 0, v125
	v_max_f32_e32 v126, 0, v126
	v_max_f32_e32 v127, 0, v127
	v_max_f32_e32 v128, 0, v128
	v_max_f32_e32 v129, 0, v129
	v_max_f32_e32 v114, 0, v114
	v_max_f32_e32 v115, 0, v115
	v_max_f32_e32 v116, 0, v116
	v_max_f32_e32 v117, 0, v117
	v_max_f32_e32 v118, 0, v118
	v_max_f32_e32 v119, 0, v119
	v_max_f32_e32 v120, 0, v120
	v_max_f32_e32 v121, 0, v121
	v_mul_f32_e32 v122, v122, v122
	v_mul_f32_e32 v123, v123, v123
	v_mul_f32_e32 v124, v124, v124
	v_mul_f32_e32 v125, v125, v125
	v_mul_f32_e32 v126, v126, v126
	v_mul_f32_e32 v127, v127, v127
	v_mul_f32_e32 v128, v128, v128
	v_mul_f32_e32 v129, v129, v129
	v_mul_f32_e32 v114, v114, v114
	v_mul_f32_e32 v115, v115, v115
	v_mul_f32_e32 v116, v116, v116
	v_mul_f32_e32 v117, v117, v117
	v_mul_f32_e32 v118, v118, v118
	v_mul_f32_e32 v119, v119, v119
	v_mul_f32_e32 v120, v120, v120
	v_mul_f32_e32 v121, v121, v121
	v_cvt_pk_bf16_f32 v126, v126, v127
	v_cvt_pk_bf16_f32 v127, v128, v129
	v_cvt_pk_bf16_f32 v128, v122, v123
	v_cvt_pk_bf16_f32 v129, v124, v125
	v_cvt_pk_bf16_f32 v118, v118, v119
	v_cvt_pk_bf16_f32 v119, v120, v121
	v_cvt_pk_bf16_f32 v120, v114, v115
	v_cvt_pk_bf16_f32 v121, v116, v117
	ds_bpermute_b32 v126, v138, v126
	ds_bpermute_b32 v127, v138, v127
	ds_bpermute_b32 v128, v138, v128
	ds_bpermute_b32 v129, v138, v129
	ds_bpermute_b32 v118, v138, v118
	ds_bpermute_b32 v119, v138, v119
	ds_bpermute_b32 v120, v138, v120
	ds_bpermute_b32 v121, v138, v121
	v_max_f32_e32 v106, 0, v106
	v_max_f32_e32 v107, 0, v107
	v_max_f32_e32 v108, 0, v108
	v_max_f32_e32 v109, 0, v109
	v_max_f32_e32 v110, 0, v110
	v_max_f32_e32 v111, 0, v111
	v_max_f32_e32 v112, 0, v112
	v_max_f32_e32 v113, 0, v113
	v_max_f32_e32 v98, 0, v98
	v_max_f32_e32 v99, 0, v99
	v_max_f32_e32 v100, 0, v100
	v_max_f32_e32 v101, 0, v101
	v_max_f32_e32 v102, 0, v102
	v_max_f32_e32 v103, 0, v103
	v_max_f32_e32 v104, 0, v104
	v_max_f32_e32 v105, 0, v105
	v_mul_f32_e32 v106, v106, v106
	v_mul_f32_e32 v107, v107, v107
	v_mul_f32_e32 v108, v108, v108
	v_mul_f32_e32 v109, v109, v109
	v_mul_f32_e32 v110, v110, v110
	v_mul_f32_e32 v111, v111, v111
	v_mul_f32_e32 v112, v112, v112
	v_mul_f32_e32 v113, v113, v113
	v_mul_f32_e32 v98, v98, v98
	v_mul_f32_e32 v99, v99, v99
	v_mul_f32_e32 v100, v100, v100
	v_mul_f32_e32 v101, v101, v101
	v_mul_f32_e32 v102, v102, v102
	v_mul_f32_e32 v103, v103, v103
	v_mul_f32_e32 v104, v104, v104
	v_mul_f32_e32 v105, v105, v105
	v_cvt_pk_bf16_f32 v110, v110, v111
	v_cvt_pk_bf16_f32 v111, v112, v113
	v_cvt_pk_bf16_f32 v112, v106, v107
	v_cvt_pk_bf16_f32 v113, v108, v109
	v_cvt_pk_bf16_f32 v102, v102, v103
	v_cvt_pk_bf16_f32 v103, v104, v105
	v_cvt_pk_bf16_f32 v104, v98, v99
	v_cvt_pk_bf16_f32 v105, v100, v101
	s_waitcnt lgkmcnt(4)
	global_store_dwordx4 v148, v[126:129], s[98:99] nt
	s_waitcnt lgkmcnt(0)
	global_store_dwordx4 v148, v[118:121], s[98:99] offset:64 nt
	ds_bpermute_b32 v110, v138, v110
	ds_bpermute_b32 v111, v138, v111
	ds_bpermute_b32 v112, v138, v112
	ds_bpermute_b32 v113, v138, v113
	ds_bpermute_b32 v102, v138, v102
	ds_bpermute_b32 v103, v138, v103
	ds_bpermute_b32 v104, v138, v104
	ds_bpermute_b32 v105, v138, v105
	v_max_f32_e32 v90, 0, v90
	v_max_f32_e32 v91, 0, v91
	v_max_f32_e32 v92, 0, v92
	v_max_f32_e32 v93, 0, v93
	v_max_f32_e32 v94, 0, v94
	v_max_f32_e32 v95, 0, v95
	v_max_f32_e32 v96, 0, v96
	v_max_f32_e32 v97, 0, v97
	v_max_f32_e32 v82, 0, v82
	v_max_f32_e32 v83, 0, v83
	v_max_f32_e32 v84, 0, v84
	v_max_f32_e32 v85, 0, v85
	v_max_f32_e32 v86, 0, v86
	v_max_f32_e32 v87, 0, v87
	v_max_f32_e32 v88, 0, v88
	v_max_f32_e32 v89, 0, v89
	v_mul_f32_e32 v90, v90, v90
	v_mul_f32_e32 v91, v91, v91
	v_mul_f32_e32 v92, v92, v92
	v_mul_f32_e32 v93, v93, v93
	v_mul_f32_e32 v94, v94, v94
	v_mul_f32_e32 v95, v95, v95
	v_mul_f32_e32 v96, v96, v96
	v_mul_f32_e32 v97, v97, v97
	v_mul_f32_e32 v82, v82, v82
	v_mul_f32_e32 v83, v83, v83
	v_mul_f32_e32 v84, v84, v84
	v_mul_f32_e32 v85, v85, v85
	v_mul_f32_e32 v86, v86, v86
	v_mul_f32_e32 v87, v87, v87
	v_mul_f32_e32 v88, v88, v88
	v_mul_f32_e32 v89, v89, v89
	v_cvt_pk_bf16_f32 v94, v94, v95
	v_cvt_pk_bf16_f32 v95, v96, v97
	v_cvt_pk_bf16_f32 v96, v90, v91
	v_cvt_pk_bf16_f32 v97, v92, v93
	v_cvt_pk_bf16_f32 v86, v86, v87
	v_cvt_pk_bf16_f32 v87, v88, v89
	v_cvt_pk_bf16_f32 v88, v82, v83
	v_cvt_pk_bf16_f32 v89, v84, v85
	s_add_u32 s98, s98, 0x20000
	s_addc_u32 s99, s99, 0
	s_waitcnt lgkmcnt(4)
	global_store_dwordx4 v148, v[110:113], s[98:99] nt
	s_waitcnt lgkmcnt(0)
	global_store_dwordx4 v148, v[102:105], s[98:99] offset:64 nt
	ds_bpermute_b32 v94, v138, v94
	ds_bpermute_b32 v95, v138, v95
	ds_bpermute_b32 v96, v138, v96
	ds_bpermute_b32 v97, v138, v97
	ds_bpermute_b32 v86, v138, v86
	ds_bpermute_b32 v87, v138, v87
	ds_bpermute_b32 v88, v138, v88
	ds_bpermute_b32 v89, v138, v89
	v_max_f32_e32 v74, 0, v74
	v_max_f32_e32 v75, 0, v75
	v_max_f32_e32 v76, 0, v76
	v_max_f32_e32 v77, 0, v77
	v_max_f32_e32 v78, 0, v78
	v_max_f32_e32 v79, 0, v79
	v_max_f32_e32 v80, 0, v80
	v_max_f32_e32 v81, 0, v81
	v_max_f32_e32 v66, 0, v66
	v_max_f32_e32 v67, 0, v67
	v_max_f32_e32 v68, 0, v68
	v_max_f32_e32 v69, 0, v69
	v_max_f32_e32 v70, 0, v70
	v_max_f32_e32 v71, 0, v71
	v_max_f32_e32 v72, 0, v72
	v_max_f32_e32 v73, 0, v73
	v_mul_f32_e32 v74, v74, v74
	v_mul_f32_e32 v75, v75, v75
	v_mul_f32_e32 v76, v76, v76
	v_mul_f32_e32 v77, v77, v77
	v_mul_f32_e32 v78, v78, v78
	v_mul_f32_e32 v79, v79, v79
	v_mul_f32_e32 v80, v80, v80
	v_mul_f32_e32 v81, v81, v81
	v_mul_f32_e32 v66, v66, v66
	v_mul_f32_e32 v67, v67, v67
	v_mul_f32_e32 v68, v68, v68
	v_mul_f32_e32 v69, v69, v69
	v_mul_f32_e32 v70, v70, v70
	v_mul_f32_e32 v71, v71, v71
	v_mul_f32_e32 v72, v72, v72
	v_mul_f32_e32 v73, v73, v73
	v_cvt_pk_bf16_f32 v78, v78, v79
	v_cvt_pk_bf16_f32 v79, v80, v81
	v_cvt_pk_bf16_f32 v80, v74, v75
	v_cvt_pk_bf16_f32 v81, v76, v77
	v_cvt_pk_bf16_f32 v70, v70, v71
	v_cvt_pk_bf16_f32 v71, v72, v73
	v_cvt_pk_bf16_f32 v72, v66, v67
	v_cvt_pk_bf16_f32 v73, v68, v69
	s_add_u32 s98, s98, 0x20000
	s_addc_u32 s99, s99, 0
	s_waitcnt lgkmcnt(4)
	global_store_dwordx4 v148, v[94:97], s[98:99] nt
	s_waitcnt lgkmcnt(0)
	global_store_dwordx4 v148, v[86:89], s[98:99] offset:64 nt
	ds_bpermute_b32 v78, v138, v78
	ds_bpermute_b32 v79, v138, v79
	ds_bpermute_b32 v80, v138, v80
	ds_bpermute_b32 v81, v138, v81
	ds_bpermute_b32 v70, v138, v70
	ds_bpermute_b32 v71, v138, v71
	ds_bpermute_b32 v72, v138, v72
	ds_bpermute_b32 v73, v138, v73
	v_max_f32_e32 v58, 0, v58
	v_max_f32_e32 v59, 0, v59
	v_max_f32_e32 v60, 0, v60
	v_max_f32_e32 v61, 0, v61
	v_max_f32_e32 v62, 0, v62
	v_max_f32_e32 v63, 0, v63
	v_max_f32_e32 v64, 0, v64
	v_max_f32_e32 v65, 0, v65
	v_max_f32_e32 v50, 0, v50
	v_max_f32_e32 v51, 0, v51
	v_max_f32_e32 v52, 0, v52
	v_max_f32_e32 v53, 0, v53
	v_max_f32_e32 v54, 0, v54
	v_max_f32_e32 v55, 0, v55
	v_max_f32_e32 v56, 0, v56
	v_max_f32_e32 v57, 0, v57
	v_mul_f32_e32 v58, v58, v58
	v_mul_f32_e32 v59, v59, v59
	v_mul_f32_e32 v60, v60, v60
	v_mul_f32_e32 v61, v61, v61
	v_mul_f32_e32 v62, v62, v62
	v_mul_f32_e32 v63, v63, v63
	v_mul_f32_e32 v64, v64, v64
	v_mul_f32_e32 v65, v65, v65
	v_mul_f32_e32 v50, v50, v50
	v_mul_f32_e32 v51, v51, v51
	v_mul_f32_e32 v52, v52, v52
	v_mul_f32_e32 v53, v53, v53
	v_mul_f32_e32 v54, v54, v54
	v_mul_f32_e32 v55, v55, v55
	v_mul_f32_e32 v56, v56, v56
	v_mul_f32_e32 v57, v57, v57
	v_cvt_pk_bf16_f32 v62, v62, v63
	v_cvt_pk_bf16_f32 v63, v64, v65
	v_cvt_pk_bf16_f32 v64, v58, v59
	v_cvt_pk_bf16_f32 v65, v60, v61
	v_cvt_pk_bf16_f32 v54, v54, v55
	v_cvt_pk_bf16_f32 v55, v56, v57
	v_cvt_pk_bf16_f32 v56, v50, v51
	v_cvt_pk_bf16_f32 v57, v52, v53
	s_add_u32 s98, s98, 0x20000
	s_addc_u32 s99, s99, 0
	s_waitcnt lgkmcnt(4)
	global_store_dwordx4 v148, v[78:81], s[98:99] nt
	s_waitcnt lgkmcnt(0)
	global_store_dwordx4 v148, v[70:73], s[98:99] offset:64 nt
	ds_bpermute_b32 v62, v138, v62
	ds_bpermute_b32 v63, v138, v63
	ds_bpermute_b32 v64, v138, v64
	ds_bpermute_b32 v65, v138, v65
	ds_bpermute_b32 v54, v138, v54
	ds_bpermute_b32 v55, v138, v55
	ds_bpermute_b32 v56, v138, v56
	ds_bpermute_b32 v57, v138, v57
	v_max_f32_e32 v42, 0, v42
	v_max_f32_e32 v43, 0, v43
	v_max_f32_e32 v44, 0, v44
	v_max_f32_e32 v45, 0, v45
	v_max_f32_e32 v46, 0, v46
	v_max_f32_e32 v47, 0, v47
	v_max_f32_e32 v48, 0, v48
	v_max_f32_e32 v49, 0, v49
	v_max_f32_e32 v34, 0, v34
	v_max_f32_e32 v35, 0, v35
	v_max_f32_e32 v36, 0, v36
	v_max_f32_e32 v37, 0, v37
	v_max_f32_e32 v38, 0, v38
	v_max_f32_e32 v39, 0, v39
	v_max_f32_e32 v40, 0, v40
	v_max_f32_e32 v41, 0, v41
	v_mul_f32_e32 v42, v42, v42
	v_mul_f32_e32 v43, v43, v43
	v_mul_f32_e32 v44, v44, v44
	v_mul_f32_e32 v45, v45, v45
	v_mul_f32_e32 v46, v46, v46
	v_mul_f32_e32 v47, v47, v47
	v_mul_f32_e32 v48, v48, v48
	v_mul_f32_e32 v49, v49, v49
	v_mul_f32_e32 v34, v34, v34
	v_mul_f32_e32 v35, v35, v35
	v_mul_f32_e32 v36, v36, v36
	v_mul_f32_e32 v37, v37, v37
	v_mul_f32_e32 v38, v38, v38
	v_mul_f32_e32 v39, v39, v39
	v_mul_f32_e32 v40, v40, v40
	v_mul_f32_e32 v41, v41, v41
	v_cvt_pk_bf16_f32 v46, v46, v47
	v_cvt_pk_bf16_f32 v47, v48, v49
	v_cvt_pk_bf16_f32 v48, v42, v43
	v_cvt_pk_bf16_f32 v49, v44, v45
	v_cvt_pk_bf16_f32 v38, v38, v39
	v_cvt_pk_bf16_f32 v39, v40, v41
	v_cvt_pk_bf16_f32 v40, v34, v35
	v_cvt_pk_bf16_f32 v41, v36, v37
	s_add_u32 s98, s98, 0xa0000
	s_addc_u32 s99, s99, 0
	s_waitcnt lgkmcnt(4)
	global_store_dwordx4 v148, v[62:65], s[98:99] nt
	s_waitcnt lgkmcnt(0)
	global_store_dwordx4 v148, v[54:57], s[98:99] offset:64 nt
	ds_bpermute_b32 v46, v138, v46
	ds_bpermute_b32 v47, v138, v47
	ds_bpermute_b32 v48, v138, v48
	ds_bpermute_b32 v49, v138, v49
	ds_bpermute_b32 v38, v138, v38
	ds_bpermute_b32 v39, v138, v39
	ds_bpermute_b32 v40, v138, v40
	ds_bpermute_b32 v41, v138, v41
	v_max_f32_e32 v26, 0, v26
	v_max_f32_e32 v27, 0, v27
	v_max_f32_e32 v28, 0, v28
	v_max_f32_e32 v29, 0, v29
	v_max_f32_e32 v30, 0, v30
	v_max_f32_e32 v31, 0, v31
	v_max_f32_e32 v32, 0, v32
	v_max_f32_e32 v33, 0, v33
	v_max_f32_e32 v18, 0, v18
	v_max_f32_e32 v19, 0, v19
	v_max_f32_e32 v20, 0, v20
	v_max_f32_e32 v21, 0, v21
	v_max_f32_e32 v22, 0, v22
	v_max_f32_e32 v23, 0, v23
	v_max_f32_e32 v24, 0, v24
	v_max_f32_e32 v25, 0, v25
	v_mul_f32_e32 v26, v26, v26
	v_mul_f32_e32 v27, v27, v27
	v_mul_f32_e32 v28, v28, v28
	v_mul_f32_e32 v29, v29, v29
	v_mul_f32_e32 v30, v30, v30
	v_mul_f32_e32 v31, v31, v31
	v_mul_f32_e32 v32, v32, v32
	v_mul_f32_e32 v33, v33, v33
	v_mul_f32_e32 v18, v18, v18
	v_mul_f32_e32 v19, v19, v19
	v_mul_f32_e32 v20, v20, v20
	v_mul_f32_e32 v21, v21, v21
	v_mul_f32_e32 v22, v22, v22
	v_mul_f32_e32 v23, v23, v23
	v_mul_f32_e32 v24, v24, v24
	v_mul_f32_e32 v25, v25, v25
	v_cvt_pk_bf16_f32 v30, v30, v31
	v_cvt_pk_bf16_f32 v31, v32, v33
	v_cvt_pk_bf16_f32 v32, v26, v27
	v_cvt_pk_bf16_f32 v33, v28, v29
	v_cvt_pk_bf16_f32 v22, v22, v23
	v_cvt_pk_bf16_f32 v23, v24, v25
	v_cvt_pk_bf16_f32 v24, v18, v19
	v_cvt_pk_bf16_f32 v25, v20, v21
	s_add_u32 s98, s98, 0x20000
	s_addc_u32 s99, s99, 0
	s_waitcnt lgkmcnt(4)
	global_store_dwordx4 v148, v[46:49], s[98:99] nt
	s_waitcnt lgkmcnt(0)
	global_store_dwordx4 v148, v[38:41], s[98:99] offset:64 nt
	ds_bpermute_b32 v30, v138, v30
	ds_bpermute_b32 v31, v138, v31
	ds_bpermute_b32 v32, v138, v32
	ds_bpermute_b32 v33, v138, v33
	ds_bpermute_b32 v22, v138, v22
	ds_bpermute_b32 v23, v138, v23
	ds_bpermute_b32 v24, v138, v24
	ds_bpermute_b32 v25, v138, v25
	v_max_f32_e32 v10, 0, v10
	v_max_f32_e32 v11, 0, v11
	v_max_f32_e32 v12, 0, v12
	v_max_f32_e32 v13, 0, v13
	v_max_f32_e32 v14, 0, v14
	v_max_f32_e32 v15, 0, v15
	v_max_f32_e32 v16, 0, v16
	v_max_f32_e32 v17, 0, v17
	v_max_f32_e32 v2, 0, v2
	v_max_f32_e32 v3, 0, v3
	v_max_f32_e32 v4, 0, v4
	v_max_f32_e32 v5, 0, v5
	v_max_f32_e32 v6, 0, v6
	v_max_f32_e32 v7, 0, v7
	v_max_f32_e32 v8, 0, v8
	v_max_f32_e32 v9, 0, v9
	v_mul_f32_e32 v10, v10, v10
	v_mul_f32_e32 v11, v11, v11
	v_mul_f32_e32 v12, v12, v12
	v_mul_f32_e32 v13, v13, v13
	v_mul_f32_e32 v14, v14, v14
	v_mul_f32_e32 v15, v15, v15
	v_mul_f32_e32 v16, v16, v16
	v_mul_f32_e32 v17, v17, v17
	v_mul_f32_e32 v2, v2, v2
	v_mul_f32_e32 v3, v3, v3
	v_mul_f32_e32 v4, v4, v4
	v_mul_f32_e32 v5, v5, v5
	v_mul_f32_e32 v6, v6, v6
	v_mul_f32_e32 v7, v7, v7
	v_mul_f32_e32 v8, v8, v8
	v_mul_f32_e32 v9, v9, v9
	v_cvt_pk_bf16_f32 v14, v14, v15
	v_cvt_pk_bf16_f32 v15, v16, v17
	v_cvt_pk_bf16_f32 v16, v10, v11
	v_cvt_pk_bf16_f32 v17, v12, v13
	v_cvt_pk_bf16_f32 v6, v6, v7
	v_cvt_pk_bf16_f32 v7, v8, v9
	v_cvt_pk_bf16_f32 v8, v2, v3
	v_cvt_pk_bf16_f32 v9, v4, v5
	s_add_u32 s98, s98, 0x20000
	s_addc_u32 s99, s99, 0
	s_waitcnt lgkmcnt(4)
	global_store_dwordx4 v148, v[30:33], s[98:99] nt
	s_waitcnt lgkmcnt(0)
	global_store_dwordx4 v148, v[22:25], s[98:99] offset:64 nt
	ds_bpermute_b32 v14, v138, v14
	ds_bpermute_b32 v15, v138, v15
	ds_bpermute_b32 v16, v138, v16
	ds_bpermute_b32 v17, v138, v17
	ds_bpermute_b32 v6, v138, v6
	ds_bpermute_b32 v7, v138, v7
	ds_bpermute_b32 v8, v138, v8
	ds_bpermute_b32 v9, v138, v9
	s_add_u32 s98, s98, 0x20000
	s_addc_u32 s99, s99, 0
	s_waitcnt lgkmcnt(4)
	global_store_dwordx4 v148, v[14:17], s[98:99] nt
	s_waitcnt lgkmcnt(0)
	global_store_dwordx4 v148, v[6:9], s[98:99] offset:64 nt
	s_andn2_b64 vcc, exec, s[0:1]
	s_mov_b64 s[0:1], -1
	s_mov_b32 s98, 1
	s_cbranch_vccnz .LBB0_772
	s_andn2_b64 vcc, exec, s[10:11]
	s_cbranch_vccnz .LBB0_771
	s_barrier
	s_branch .LBB0_771
